# first grid barrier: read the 16 per-XCD arrival counters with one wait instead of 16
# baseline (speedup 1.0000x reference)
.LBB0_113:
	v_readlane_b32 s4, v250, 55
	v_readlane_b32 s5, v250, 56
	s_waitcnt lgkmcnt(0)
	global_load_dword v0, v65, s[58:59] sc1
	v_readlane_b32 s6, v253, 21
	s_nop 1
	global_load_dword v1, v65, s[4:5] sc1
	v_readlane_b32 s4, v250, 57
	v_readlane_b32 s5, v250, 58
	s_nop 4
	global_load_dword v2, v65, s[4:5] sc1
	v_readlane_b32 s4, v250, 59
	v_readlane_b32 s5, v250, 60
	s_nop 4
	global_load_dword v3, v65, s[4:5] sc1
	v_readlane_b32 s4, v250, 61
	v_readlane_b32 s5, v250, 62
	s_nop 4
	global_load_dword v4, v65, s[4:5] sc1
	v_readlane_b32 s4, v250, 63
	v_readlane_b32 s5, v251, 0
	s_nop 4
	global_load_dword v5, v65, s[4:5] sc1
	v_readlane_b32 s4, v251, 1
	v_readlane_b32 s5, v251, 2
	s_nop 4
	global_load_dword v6, v65, s[4:5] sc1
	v_readlane_b32 s4, v251, 3
	v_readlane_b32 s5, v251, 4
	s_nop 4
	global_load_dword v7, v65, s[4:5] sc1
	v_readlane_b32 s4, v251, 5
	v_readlane_b32 s5, v251, 6
	s_nop 4
	global_load_dword v8, v65, s[4:5] sc1
	v_readlane_b32 s4, v251, 7
	v_readlane_b32 s5, v251, 8
	s_nop 4
	global_load_dword v9, v65, s[4:5] sc1
	v_readlane_b32 s4, v251, 9
	v_readlane_b32 s5, v251, 10
	s_nop 4
	global_load_dword v10, v65, s[4:5] sc1
	v_readlane_b32 s4, v251, 11
	v_readlane_b32 s5, v251, 12
	s_nop 4
	global_load_dword v11, v65, s[4:5] sc1
	v_readlane_b32 s4, v251, 13
	v_readlane_b32 s5, v251, 14
	s_nop 4
	global_load_dword v12, v65, s[4:5] sc1
	v_readlane_b32 s4, v251, 15
	v_readlane_b32 s5, v251, 16
	s_nop 4
	global_load_dword v13, v65, s[4:5] sc1
	v_readlane_b32 s4, v251, 17
	v_readlane_b32 s5, v251, 18
	s_nop 4
	global_load_dword v14, v65, s[4:5] sc1
	v_readlane_b32 s4, v251, 19
	v_readlane_b32 s5, v251, 20
	s_nop 4
	global_load_dword v15, v65, s[4:5] sc1
	s_mov_b64 s[4:5], -1
	s_waitcnt vmcnt(0)
	v_add_u32_e32 v16, v1, v0
	v_add_u32_e32 v16, v16, v2
	v_add_u32_e32 v16, v16, v3
	v_add_u32_e32 v16, v16, v4
	v_add_u32_e32 v16, v16, v5
	v_add_u32_e32 v16, v16, v6
	v_add_u32_e32 v16, v16, v7
	v_add_u32_e32 v16, v16, v8
	v_add_u32_e32 v16, v16, v9
	v_add_u32_e32 v16, v16, v10
	v_add_u32_e32 v16, v16, v11
	v_add_u32_e32 v16, v16, v12
	v_add_u32_e32 v16, v16, v13
	v_add_u32_e32 v16, v16, v14
	v_add_u32_e32 v16, v16, v15
	v_cmp_eq_u32_e32 vcc, s6, v16
	s_mov_b64 s[6:7], -1
	s_cbranch_vccnz .LBB0_112
	s_and_b32 s4, s3, 0xff
	s_cmp_eq_u32 s4, 0
	s_mov_b64 s[4:5], -1
	s_mov_b64 s[8:9], -1
	s_sleep 1
	s_cbranch_scc0 .LBB0_117
	global_load_dword v16, v65, s[44:45] sc1
	s_waitcnt vmcnt(0)
	v_cmp_eq_u32_e32 vcc, 0, v16
	s_cbranch_vccnz .LBB0_119
	s_mov_b64 s[8:9], 0
